# speedup vs baseline: 1.0017x; 1.0017x over previous
; __device__ __forceinline__ float bflo(unsigned u) { return __uint_as_float(u << 16); }
; __device__ __forceinline__ void nsa_item2(const Params& p, int item, char* lds, unsigned* lds_um, int tid) {
;     ...
;   const float gwa = 1.0f / (1.0f + __expf(-bflo((unsigned)grow[32]))), gwb = 1.0f / (1.0f + __expf(-bflo((unsigned)grow[33])));
;     ...
;   {
;     float la = lsa + __shfl_xor(lsa, 16); la += __shfl_xor(la, 32);
;     float lb = lsb + __shfl_xor(lsb, 16); lb += __shfl_xor(lb, 32);
;     const float fa = gwa / la, fb = gwb / lb;
;     u16* mixa = WSP(u16, WS_MIX) + ((long)(b * 2048 + t)) * D + 2048 + ha * 128 + fq * 4;
; #pragma unroll
;     for (int dt = 0; dt < 8; ++dt) {
;       f32x4 pa = *reinterpret_cast<const f32x4*>(Pa + 16 * dt), pb = *reinterpret_cast<const f32x4*>(Pb + 16 * dt);
; #pragma unroll
;       for (int j = 0; j < 4; ++j) { pa[j] += oa[dt][j] * fa; pb[j] += ob[dt][j] * fb; }
;       *reinterpret_cast<u32x2*>(mixa + 16 * dt) = u32x2{pk2(pa[0], pa[1]), pk2(pa[2], pa[3])};
;       *reinterpret_cast<u32x2*>(mixa + 128 + 16 * dt) = u32x2{pk2(pb[0], pb[1]), pk2(pb[2], pb[3])};
;     }
;   }
.LBB0_59:
	global_load_dwordx4 v[104:107], v[126:127], off offset:0
	global_load_dwordx4 v[108:111], v[126:127], off offset:512
	global_load_dwordx4 v[116:119], v[126:127], off offset:64
	global_load_dwordx4 v[120:123], v[126:127], off offset:576
	global_load_dwordx4 v[208:211], v[126:127], off offset:128
	global_load_dwordx4 v[212:215], v[126:127], off offset:640
	global_load_dwordx4 v[216:219], v[126:127], off offset:192
	global_load_dwordx4 v[220:223], v[126:127], off offset:704
	global_load_dwordx4 v[224:227], v[126:127], off offset:256
	global_load_dwordx4 v[228:231], v[126:127], off offset:768
	global_load_dwordx4 v[232:235], v[126:127], off offset:320
	global_load_dwordx4 v[240:243], v[126:127], off offset:832
	v_and_b32_e32 v0, 0xffff0000, v137
	v_mul_f32_e32 v0, 0xbfb8aa3b, v0
	v_exp_f32_e32 v0, v0
	s_nop 0
	v_add_f32_e32 v0, 1.0, v0
	v_div_scale_f32 v3, s[0:1], v0, v0, 1.0
	v_rcp_f32_e32 v4, v3
	s_nop 0
	v_fma_f32 v5, -v3, v4, 1.0
	v_fmac_f32_e32 v4, v5, v4
	v_div_scale_f32 v5, vcc, 1.0, v0, 1.0
	v_mul_f32_e32 v6, v5, v4
	v_fma_f32 v7, -v3, v6, v5
	v_fmac_f32_e32 v6, v7, v4
	v_fma_f32 v3, -v3, v6, v5
	v_div_fmas_f32 v3, v3, v4, v6
	v_div_fixup_f32 v0, v3, v0, 1.0
	v_lshlrev_b32_e32 v3, 16, v137
	v_mul_f32_e32 v3, 0xbfb8aa3b, v3
	v_exp_f32_e32 v3, v3
	s_nop 0
	v_add_f32_e32 v3, 1.0, v3
	v_div_scale_f32 v4, s[0:1], v3, v3, 1.0
	v_rcp_f32_e32 v5, v4
	s_nop 0
	v_fma_f32 v6, -v4, v5, 1.0
	v_fmac_f32_e32 v5, v6, v5
	v_div_scale_f32 v6, vcc, 1.0, v3, 1.0
	v_mul_f32_e32 v7, v6, v5
	v_fma_f32 v8, -v4, v7, v6
	v_fmac_f32_e32 v7, v8, v5
	v_fma_f32 v4, -v4, v7, v6
	v_div_fmas_f32 v4, v4, v5, v7
	v_div_fixup_f32 v3, v4, v3, 1.0
	ds_bpermute_b32 v4, v124, v205
	s_waitcnt lgkmcnt(0)
	v_add_f32_e32 v4, v205, v4
	ds_bpermute_b32 v5, v144, v4
	s_waitcnt lgkmcnt(0)
	v_add_f32_e32 v4, v4, v5
	ds_bpermute_b32 v5, v124, v2
	s_waitcnt lgkmcnt(0)
	v_add_f32_e32 v2, v2, v5
	ds_bpermute_b32 v5, v144, v2
	s_waitcnt lgkmcnt(0)
	v_add_f32_e32 v2, v2, v5
	v_div_scale_f32 v5, s[0:1], v4, v4, v3
	v_rcp_f32_e32 v6, v5
	s_nop 0
	v_fma_f32 v7, -v5, v6, 1.0
	v_fmac_f32_e32 v6, v7, v6
	v_div_scale_f32 v7, vcc, v3, v4, v3
	v_mul_f32_e32 v8, v7, v6
	v_fma_f32 v9, -v5, v8, v7
	v_fmac_f32_e32 v8, v9, v6
	v_fma_f32 v5, -v5, v8, v7
	v_div_fmas_f32 v5, v5, v6, v8
	v_div_fixup_f32 v12, v5, v4, v3
	v_div_scale_f32 v3, s[0:1], v2, v2, v0
	v_rcp_f32_e32 v4, v3
	s_mov_b64 s[0:1], 0x17211000
	v_fma_f32 v5, -v3, v4, 1.0
	v_fmac_f32_e32 v4, v5, v4
	v_div_scale_f32 v5, vcc, v0, v2, v0
	v_mul_f32_e32 v6, v5, v4
	v_fma_f32 v7, -v3, v6, v5
	v_fmac_f32_e32 v6, v7, v4
	v_fma_f32 v3, -v3, v6, v5
	v_div_fmas_f32 v3, v3, v4, v6
	v_div_fixup_f32 v13, v3, v2, v0
	v_lshl_add_u64 v[2:3], s[82:83], 0, v[128:129]
	v_lshlrev_b32_e32 v0, 1, v148
	v_lshl_add_u64 v[2:3], v[2:3], 0, v[0:1]
	v_lshlrev_b32_e32 v0, 1, v145
	v_lshl_add_u64 v[14:15], v[2:3], 0, v[0:1]
	v_lshl_add_u64 v[10:11], v[14:15], 0, s[0:1]
	s_waitcnt vmcnt(0) lgkmcnt(0)
; __device__ __forceinline__ void nsa_item2(const Params& p, int item, char* lds, unsigned* lds_um, int tid) {
;     ...
;     u16* mixa = WSP(u16, WS_MIX) + ((long)(b * 2048 + t)) * D + 2048 + ha * 128 + fq * 4;
; #pragma unroll
;     for (int dt = 0; dt < 8; ++dt) {
;       f32x4 pa = *reinterpret_cast<const f32x4*>(Pa + 16 * dt), pb = *reinterpret_cast<const f32x4*>(Pb + 16 * dt);
; #pragma unroll
;       for (int j = 0; j < 4; ++j) { pa[j] += oa[dt][j] * fa; pb[j] += ob[dt][j] * fb; }
;       *reinterpret_cast<u32x2*>(mixa + 16 * dt) = u32x2{pk2(pa[0], pa[1]), pk2(pa[2], pa[3])};
;       *reinterpret_cast<u32x2*>(mixa + 128 + 16 * dt) = u32x2{pk2(pb[0], pb[1]), pk2(pb[2], pb[3])};
;     }
	v_fma_f32 v92, v92, v12, v104
	v_fma_f32 v93, v93, v12, v105
	v_fma_f32 v94, v94, v12, v106
	v_fma_f32 v95, v95, v12, v107
	v_fma_f32 v96, v96, v13, v108
	v_fma_f32 v97, v97, v13, v109
	v_fma_f32 v98, v98, v13, v110
	v_fma_f32 v99, v99, v13, v111
	v_cvt_pk_bf16_f32 v92, v92, v93
	v_cvt_pk_bf16_f32 v93, v94, v95
	v_cvt_pk_bf16_f32 v96, v96, v97
	v_cvt_pk_bf16_f32 v97, v98, v99
	global_store_dwordx2 v[10:11], v[92:93], off offset:0
	global_store_dwordx2 v[10:11], v[96:97], off offset:256
	v_fma_f32 v84, v84, v12, v116
	v_fma_f32 v85, v85, v12, v117
	v_fma_f32 v86, v86, v12, v118
	v_fma_f32 v87, v87, v12, v119
	v_fma_f32 v88, v88, v13, v120
	v_fma_f32 v89, v89, v13, v121
	v_fma_f32 v90, v90, v13, v122
	v_fma_f32 v91, v91, v13, v123
	v_cvt_pk_bf16_f32 v84, v84, v85
	v_cvt_pk_bf16_f32 v85, v86, v87
	v_cvt_pk_bf16_f32 v88, v88, v89
	v_cvt_pk_bf16_f32 v89, v90, v91
	global_store_dwordx2 v[10:11], v[84:85], off offset:32
	global_store_dwordx2 v[10:11], v[88:89], off offset:288
	global_load_dwordx4 v[104:107], v[126:127], off offset:384
	global_load_dwordx4 v[108:111], v[126:127], off offset:896
	global_load_dwordx4 v[116:119], v[126:127], off offset:448
	global_load_dwordx4 v[120:123], v[126:127], off offset:960
	v_fma_f32 v76, v76, v12, v208
	v_fma_f32 v77, v77, v12, v209
	v_fma_f32 v78, v78, v12, v210
	v_fma_f32 v79, v79, v12, v211
	v_fma_f32 v80, v80, v13, v212
	v_fma_f32 v81, v81, v13, v213
	v_fma_f32 v82, v82, v13, v214
	v_fma_f32 v83, v83, v13, v215
	v_cvt_pk_bf16_f32 v76, v76, v77
	v_cvt_pk_bf16_f32 v77, v78, v79
	v_cvt_pk_bf16_f32 v80, v80, v81
	v_cvt_pk_bf16_f32 v81, v82, v83
	global_store_dwordx2 v[10:11], v[76:77], off offset:64
	global_store_dwordx2 v[10:11], v[80:81], off offset:320
	v_fma_f32 v68, v68, v12, v216
	v_fma_f32 v69, v69, v12, v217
	v_fma_f32 v70, v70, v12, v218
	v_fma_f32 v71, v71, v12, v219
	v_fma_f32 v72, v72, v13, v220
	v_fma_f32 v73, v73, v13, v221
	v_fma_f32 v74, v74, v13, v222
	v_fma_f32 v75, v75, v13, v223
	v_cvt_pk_bf16_f32 v68, v68, v69
	v_cvt_pk_bf16_f32 v69, v70, v71
	v_cvt_pk_bf16_f32 v72, v72, v73
	v_cvt_pk_bf16_f32 v73, v74, v75
	global_store_dwordx2 v[10:11], v[68:69], off offset:96
	global_store_dwordx2 v[10:11], v[72:73], off offset:352
	v_fma_f32 v60, v60, v12, v224
	v_fma_f32 v61, v61, v12, v225
	v_fma_f32 v62, v62, v12, v226
	v_fma_f32 v63, v63, v12, v227
	v_fma_f32 v64, v64, v13, v228
	v_fma_f32 v65, v65, v13, v229
	v_fma_f32 v66, v66, v13, v230
	v_fma_f32 v67, v67, v13, v231
	v_cvt_pk_bf16_f32 v60, v60, v61
	v_cvt_pk_bf16_f32 v61, v62, v63
	v_cvt_pk_bf16_f32 v64, v64, v65
	v_cvt_pk_bf16_f32 v65, v66, v67
	global_store_dwordx2 v[10:11], v[60:61], off offset:128
	global_store_dwordx2 v[10:11], v[64:65], off offset:384
	v_fma_f32 v52, v52, v12, v232
	v_fma_f32 v53, v53, v12, v233
	v_fma_f32 v54, v54, v12, v234
	v_fma_f32 v55, v55, v12, v235
	v_fma_f32 v56, v56, v13, v240
	v_fma_f32 v57, v57, v13, v241
	v_fma_f32 v58, v58, v13, v242
	v_fma_f32 v59, v59, v13, v243
	v_cvt_pk_bf16_f32 v52, v52, v53
	v_cvt_pk_bf16_f32 v53, v54, v55
	v_cvt_pk_bf16_f32 v56, v56, v57
	v_cvt_pk_bf16_f32 v57, v58, v59
	global_store_dwordx2 v[10:11], v[52:53], off offset:160
	global_store_dwordx2 v[10:11], v[56:57], off offset:416
	s_waitcnt vmcnt(8)
	v_fma_f32 v44, v44, v12, v104
	v_fma_f32 v45, v45, v12, v105
	v_fma_f32 v46, v46, v12, v106
	v_fma_f32 v47, v47, v12, v107
	v_fma_f32 v48, v48, v13, v108
	v_fma_f32 v49, v49, v13, v109
	v_fma_f32 v50, v50, v13, v110
	v_fma_f32 v51, v51, v13, v111
	v_cvt_pk_bf16_f32 v44, v44, v45
	v_cvt_pk_bf16_f32 v45, v46, v47
	v_cvt_pk_bf16_f32 v48, v48, v49
	v_cvt_pk_bf16_f32 v49, v50, v51
	global_store_dwordx2 v[10:11], v[44:45], off offset:192
	global_store_dwordx2 v[10:11], v[48:49], off offset:448
	v_fma_f32 v36, v36, v12, v116
	v_fma_f32 v37, v37, v12, v117
	v_fma_f32 v38, v38, v12, v118
	v_fma_f32 v39, v39, v12, v119
	v_fma_f32 v40, v40, v13, v120
	v_fma_f32 v41, v41, v13, v121
	v_fma_f32 v42, v42, v13, v122
	v_fma_f32 v43, v43, v13, v123
	v_cvt_pk_bf16_f32 v36, v36, v37
	v_cvt_pk_bf16_f32 v37, v38, v39
	v_cvt_pk_bf16_f32 v40, v40, v41
	v_cvt_pk_bf16_f32 v41, v42, v43
	global_store_dwordx2 v[10:11], v[36:37], off offset:224
	global_store_dwordx2 v[10:11], v[40:41], off offset:480
	s_mov_b64 s[0:1], 0
	s_waitcnt lgkmcnt(0)
	s_barrier

; __device__ __forceinline__ void nsa_item2(const Params& p, int item, char* lds, unsigned* lds_um, int tid) {
;     ...
;     if (i == nslc) {
;       float la = lsa + __shfl_xor(lsa, 16); la += __shfl_xor(la, 32);
;       float lb = lsb + __shfl_xor(lsb, 16); lb += __shfl_xor(lb, 32);
;       const float fa = gsa / la, fb = gsb / lb;
; #pragma unroll
;       for (int dt = 0; dt < 8; ++dt) {
;         f32x4 pa = *reinterpret_cast<const f32x4*>(Pa + 16 * dt), pb = *reinterpret_cast<const f32x4*>(Pb + 16 * dt);
; #pragma unroll
;         for (int j = 0; j < 4; ++j) { pa[j] += oa[dt][j] * fa; pb[j] += ob[dt][j] * fb; oa[dt][j] = 0.f; ob[dt][j] = 0.f; }
;         *reinterpret_cast<f32x4*>(Pa + 16 * dt) = pa;
;         *reinterpret_cast<f32x4*>(Pb + 16 * dt) = pb;
;       }
;       ma = -1e30f; mb = -1e30f; lsa = 0.f; lsb = 0.f;
;     }
.LBB0_165:
	global_load_dwordx4 v[104:107], v[126:127], off offset:0
	global_load_dwordx4 v[108:111], v[126:127], off offset:512
	global_load_dwordx4 v[116:119], v[126:127], off offset:64
	global_load_dwordx4 v[120:123], v[126:127], off offset:576
	global_load_dwordx4 v[208:211], v[126:127], off offset:128
	global_load_dwordx4 v[212:215], v[126:127], off offset:640
	global_load_dwordx4 v[216:219], v[126:127], off offset:192
	global_load_dwordx4 v[220:223], v[126:127], off offset:704
	global_load_dwordx4 v[224:227], v[126:127], off offset:256
	global_load_dwordx4 v[228:231], v[126:127], off offset:768
	global_load_dwordx4 v[232:235], v[126:127], off offset:320
	global_load_dwordx4 v[240:243], v[126:127], off offset:832
	ds_bpermute_b32 v0, v124, v205
	v_mov_b32_e32 v206, 0xf149f2ca
	s_waitcnt lgkmcnt(0)
	v_add_f32_e32 v0, v205, v0
	ds_bpermute_b32 v3, v144, v0
	v_mov_b32_e32 v205, 0
	s_waitcnt lgkmcnt(0)
	v_add_f32_e32 v0, v0, v3
	ds_bpermute_b32 v3, v124, v2
	s_waitcnt lgkmcnt(0)
	v_add_f32_e32 v2, v2, v3
	ds_bpermute_b32 v3, v144, v2
	s_waitcnt lgkmcnt(0)
	v_add_f32_e32 v2, v2, v3
	v_div_scale_f32 v3, s[0:1], v0, v0, v152
	v_rcp_f32_e32 v100, v3
	s_nop 0
	v_fma_f32 v101, -v3, v100, 1.0
	v_fmac_f32_e32 v100, v101, v100
	v_div_scale_f32 v101, vcc, v152, v0, v152
	v_mul_f32_e32 v102, v101, v100
	v_fma_f32 v103, -v3, v102, v101
	v_fmac_f32_e32 v102, v103, v100
	v_fma_f32 v3, -v3, v102, v101
	v_div_fmas_f32 v3, v3, v100, v102
	v_div_fixup_f32 v0, v3, v0, v152
	v_div_scale_f32 v3, s[0:1], v2, v2, v153
	v_rcp_f32_e32 v100, v3
	s_nop 0
	v_fma_f32 v101, -v3, v100, 1.0
	v_fmac_f32_e32 v100, v101, v100
	v_div_scale_f32 v101, vcc, v153, v2, v153
	v_mul_f32_e32 v102, v101, v100
	v_fma_f32 v103, -v3, v102, v101
	v_fmac_f32_e32 v102, v103, v100
	v_fma_f32 v3, -v3, v102, v101
	v_div_fmas_f32 v3, v3, v100, v102
	v_div_fixup_f32 v2, v3, v2, v153
	s_waitcnt vmcnt(0) lgkmcnt(0)
	v_pk_fma_f32 v[92:93], v[92:93], v[0:1], v[104:105] op_sel_hi:[1,0,1]
	v_pk_fma_f32 v[94:95], v[94:95], v[0:1], v[106:107] op_sel_hi:[1,0,1]
	v_pk_fma_f32 v[96:97], v[96:97], v[2:3], v[108:109] op_sel_hi:[1,0,1]
	v_pk_fma_f32 v[98:99], v[98:99], v[2:3], v[110:111] op_sel_hi:[1,0,1]
	global_store_dwordx4 v[126:127], v[92:95], off offset:0
	global_store_dwordx4 v[126:127], v[96:99], off offset:512
	v_pk_fma_f32 v[84:85], v[84:85], v[0:1], v[116:117] op_sel_hi:[1,0,1]
	v_pk_fma_f32 v[86:87], v[86:87], v[0:1], v[118:119] op_sel_hi:[1,0,1]
	v_pk_fma_f32 v[88:89], v[88:89], v[2:3], v[120:121] op_sel_hi:[1,0,1]
	v_pk_fma_f32 v[90:91], v[90:91], v[2:3], v[122:123] op_sel_hi:[1,0,1]
	global_store_dwordx4 v[126:127], v[84:87], off offset:64
	global_store_dwordx4 v[126:127], v[88:91], off offset:576
	global_load_dwordx4 v[104:107], v[126:127], off offset:384
	global_load_dwordx4 v[108:111], v[126:127], off offset:896
	global_load_dwordx4 v[116:119], v[126:127], off offset:448
	global_load_dwordx4 v[120:123], v[126:127], off offset:960
	v_pk_fma_f32 v[76:77], v[76:77], v[0:1], v[208:209] op_sel_hi:[1,0,1]
	v_pk_fma_f32 v[78:79], v[78:79], v[0:1], v[210:211] op_sel_hi:[1,0,1]
	v_pk_fma_f32 v[80:81], v[80:81], v[2:3], v[212:213] op_sel_hi:[1,0,1]
	v_pk_fma_f32 v[82:83], v[82:83], v[2:3], v[214:215] op_sel_hi:[1,0,1]
	global_store_dwordx4 v[126:127], v[76:79], off offset:128
	global_store_dwordx4 v[126:127], v[80:83], off offset:640
	v_pk_fma_f32 v[68:69], v[68:69], v[0:1], v[216:217] op_sel_hi:[1,0,1]
	v_pk_fma_f32 v[70:71], v[70:71], v[0:1], v[218:219] op_sel_hi:[1,0,1]
	v_pk_fma_f32 v[72:73], v[72:73], v[2:3], v[220:221] op_sel_hi:[1,0,1]
	v_pk_fma_f32 v[74:75], v[74:75], v[2:3], v[222:223] op_sel_hi:[1,0,1]
	global_store_dwordx4 v[126:127], v[68:71], off offset:192
	global_store_dwordx4 v[126:127], v[72:75], off offset:704
	v_pk_fma_f32 v[60:61], v[60:61], v[0:1], v[224:225] op_sel_hi:[1,0,1]
	v_pk_fma_f32 v[62:63], v[62:63], v[0:1], v[226:227] op_sel_hi:[1,0,1]
	v_pk_fma_f32 v[64:65], v[64:65], v[2:3], v[228:229] op_sel_hi:[1,0,1]
	v_pk_fma_f32 v[66:67], v[66:67], v[2:3], v[230:231] op_sel_hi:[1,0,1]
	global_store_dwordx4 v[126:127], v[60:63], off offset:256
	global_store_dwordx4 v[126:127], v[64:67], off offset:768
	v_pk_fma_f32 v[52:53], v[52:53], v[0:1], v[232:233] op_sel_hi:[1,0,1]
	v_pk_fma_f32 v[54:55], v[54:55], v[0:1], v[234:235] op_sel_hi:[1,0,1]
	v_pk_fma_f32 v[56:57], v[56:57], v[2:3], v[240:241] op_sel_hi:[1,0,1]
	v_pk_fma_f32 v[58:59], v[58:59], v[2:3], v[242:243] op_sel_hi:[1,0,1]
	global_store_dwordx4 v[126:127], v[52:55], off offset:320
	global_store_dwordx4 v[126:127], v[56:59], off offset:832
	s_waitcnt vmcnt(8)
	v_pk_fma_f32 v[44:45], v[44:45], v[0:1], v[104:105] op_sel_hi:[1,0,1]
	v_pk_fma_f32 v[46:47], v[46:47], v[0:1], v[106:107] op_sel_hi:[1,0,1]
	v_pk_fma_f32 v[48:49], v[48:49], v[2:3], v[108:109] op_sel_hi:[1,0,1]
	v_pk_fma_f32 v[50:51], v[50:51], v[2:3], v[110:111] op_sel_hi:[1,0,1]
	global_store_dwordx4 v[126:127], v[44:47], off offset:384
	global_store_dwordx4 v[126:127], v[48:51], off offset:896
	v_pk_fma_f32 v[36:37], v[36:37], v[0:1], v[116:117] op_sel_hi:[1,0,1]
	v_pk_fma_f32 v[38:39], v[38:39], v[0:1], v[118:119] op_sel_hi:[1,0,1]
	v_pk_fma_f32 v[40:41], v[40:41], v[2:3], v[120:121] op_sel_hi:[1,0,1]
	v_pk_fma_f32 v[42:43], v[42:43], v[2:3], v[122:123] op_sel_hi:[1,0,1]
	global_store_dwordx4 v[126:127], v[36:39], off offset:448
	global_store_dwordx4 v[126:127], v[40:43], off offset:960
	s_nop 1
	v_mov_b32_e32 v36, 0
	v_mov_b32_e32 v37, 0
	v_mov_b32_e32 v38, 0
	v_mov_b32_e32 v39, 0
	v_mov_b32_e32 v40, 0
	v_mov_b32_e32 v41, 0
	v_mov_b32_e32 v42, 0
	v_mov_b32_e32 v43, 0
	v_mov_b32_e32 v44, 0
	v_mov_b32_e32 v45, 0
	v_mov_b32_e32 v46, 0
	v_mov_b32_e32 v47, 0
	v_mov_b32_e32 v48, 0
	v_mov_b32_e32 v49, 0
	v_mov_b32_e32 v50, 0
	v_mov_b32_e32 v51, 0
	v_mov_b32_e32 v52, 0
	v_mov_b32_e32 v53, 0
	v_mov_b32_e32 v54, 0
	v_mov_b32_e32 v55, 0
	v_mov_b32_e32 v56, 0
	v_mov_b32_e32 v57, 0
	v_mov_b32_e32 v58, 0
	v_mov_b32_e32 v59, 0
	v_mov_b32_e32 v60, 0
	v_mov_b32_e32 v61, 0
	v_mov_b32_e32 v62, 0
	v_mov_b32_e32 v63, 0
	v_mov_b32_e32 v64, 0
	v_mov_b32_e32 v65, 0
	v_mov_b32_e32 v66, 0
	v_mov_b32_e32 v67, 0
	v_mov_b32_e32 v68, 0
	v_mov_b32_e32 v69, 0
	v_mov_b32_e32 v70, 0
	v_mov_b32_e32 v71, 0
	v_mov_b32_e32 v72, 0
	v_mov_b32_e32 v73, 0
	v_mov_b32_e32 v74, 0
	v_mov_b32_e32 v75, 0
	v_mov_b32_e32 v76, 0
	v_mov_b32_e32 v77, 0
	v_mov_b32_e32 v78, 0
	v_mov_b32_e32 v79, 0
	v_mov_b32_e32 v80, 0
	v_mov_b32_e32 v81, 0
	v_mov_b32_e32 v82, 0
	v_mov_b32_e32 v83, 0
	v_mov_b32_e32 v84, 0
	v_mov_b32_e32 v85, 0
	v_mov_b32_e32 v86, 0
	v_mov_b32_e32 v87, 0
	v_mov_b32_e32 v88, 0
	v_mov_b32_e32 v89, 0
	v_mov_b32_e32 v90, 0
	v_mov_b32_e32 v91, 0
	v_mov_b32_e32 v92, 0
	v_mov_b32_e32 v93, 0
	v_mov_b32_e32 v94, 0
	v_mov_b32_e32 v95, 0
	v_mov_b32_e32 v96, 0
	v_mov_b32_e32 v97, 0
	v_mov_b32_e32 v98, 0
	v_mov_b32_e32 v99, 0
	v_mov_b32_e32 v0, v1
	v_mov_b32_e32 v3, 0xf149f2ca
	v_mov_b32_e32 v2, 0
